# attention work queue: next unit's index fetched during the current unit's last pair (FoX) / window compute (SB)
# speedup vs baseline: 1.0049x; 1.0010x over previous
; #define LAS3 __attribute__((address_space(3)))
; #define ATT_WAIT_BAR() asm volatile("s_waitcnt vmcnt(0) lgkmcnt(0)\n\ts_barrier" ::: "memory")
; __device__ __forceinline__ void sb_unit(int b, int hh, int qb, const bf16_t* Q, const bf16_t* __restrict__ K, const bf16_t* __restrict__ V, bf16_t* O, float* SS, LAS3 unsigned char* shm) {
;     ...
;     volatile LAS3 unsigned char* fbytes = (volatile LAS3 unsigned char*)(shm + L_FLAG);
;     asm volatile("" :: "v"(qr[0]), "v"(qr[1]), "v"(qr[2]), "v"(qr[3]));
;     ATT_WAIT_BAR();
;     ...
;         sb_tile(shm + (jt - T_lo) * SLOTB + kl, shm + WV + (jt - T_lo) * SLOTB + vl, jt, qw0, r32, hi, qr, carry, o0, o1);
;         if (!__any(carry != 0.f)) break;
; __global__ void __launch_bounds__(NWAVES * 64, 2) fwd_megakernel(Args args) {
;     ...
;             if (tid == 0) qw[0] = atomicAdd(CTL, 1u);
.LBB0_368:
	s_lshl_b32 s0, s0, 8
	s_lshl_b32 s33, s5, 5
	s_lshl_b32 s1, s1, 13
	s_add_i32 s86, s33, s0
	s_add_i32 s78, s86, s1
	s_mov_b32 s79, s81
	s_lshl_b32 s6, s6, 6
	s_lshl_b64 s[0:1], s[78:79], 11
	v_readlane_b32 s10, v249, 23
	v_readlane_b32 s11, v249, 24
	s_add_u32 s0, s10, s0
	s_addc_u32 s1, s11, s1
	s_lshl_b32 s85, s6, 1
	s_add_u32 s0, s0, s85
	s_addc_u32 s1, s1, 0
	v_lshlrev_b32_e32 v2, 1, v134
	v_lshl_add_u64 v[4:5], s[0:1], 0, v[2:3]
	v_lshlrev_b32_e32 v2, 1, v136
	v_lshl_add_u64 v[4:5], v[4:5], 0, v[2:3]
	global_load_dwordx4 v[82:85], v[4:5], off
	global_load_dwordx4 v[86:89], v[4:5], off offset:32
	global_load_dwordx4 v[90:93], v[4:5], off offset:64
	global_load_dwordx4 v[94:97], v[4:5], off offset:96
	s_lshr_b32 s10, s86, 6
	s_cmp_ge_i32 s10, s3
	s_waitcnt vmcnt(0)
	s_waitcnt vmcnt(0) lgkmcnt(0)
	s_barrier
	s_cbranch_scc0 .LBB0_374
	s_mov_b64 s[98:99], exec
	v_readlane_b32 s100, v249, 10
	v_readlane_b32 s101, v249, 11
	s_nop 0
	s_and_b64 exec, s[98:99], s[100:101]
	s_cbranch_execz .Lqpf_skip2
	v_readlane_b32 s100, v249, 43
	v_readlane_b32 s101, v249, 44
	v_mov_b32_e32 v187, 1
	s_nop 3
	global_atomic_add v187, v3, v187, s[100:101] sc0
.Lqpf_skip2:
	s_mov_b64 exec, s[98:99]
	s_lshl_b32 s0, s2, 8
	s_lshl_b32 s1, s10, 6
	s_add_i32 s0, s1, s0
	v_add_u32_e32 v2, s0, v168
	s_lshl_b32 s0, s3, 13
	v_mov_b32_e32 v18, 0
	v_subrev_u32_e32 v2, s33, v2
	s_or_b32 s6, s1, 63
	s_lshl_b32 s7, s10, 13
	v_subrev_u32_e32 v102, s0, v139
	v_subrev_u32_e32 v104, s0, v169
	v_mov_b32_e32 v5, 1.0
	v_mov_b32_e32 v19, v18
	v_mov_b32_e32 v20, v18
	v_mov_b32_e32 v21, v18
	v_mov_b32_e32 v22, v18
	v_mov_b32_e32 v23, v18
	v_mov_b32_e32 v24, v18
	v_mov_b32_e32 v25, v18
	v_mov_b32_e32 v26, v18
	v_mov_b32_e32 v27, v18
	v_mov_b32_e32 v28, v18
	v_mov_b32_e32 v29, v18
	v_mov_b32_e32 v30, v18
	v_mov_b32_e32 v31, v18
	v_mov_b32_e32 v32, v18
	v_mov_b32_e32 v33, v18
	v_mov_b32_e32 v34, v18
	v_mov_b32_e32 v35, v18
	v_mov_b32_e32 v36, v18
	v_mov_b32_e32 v37, v18
	v_mov_b32_e32 v38, v18
	v_mov_b32_e32 v39, v18
	v_mov_b32_e32 v40, v18
	v_mov_b32_e32 v41, v18
	v_mov_b32_e32 v42, v18
	v_mov_b32_e32 v43, v18
	v_mov_b32_e32 v44, v18
	v_mov_b32_e32 v45, v18
	v_mov_b32_e32 v46, v18
	v_mov_b32_e32 v47, v18
	v_mov_b32_e32 v48, v18
	v_mov_b32_e32 v49, v18

; #define LAS3 __attribute__((address_space(3)))
; __device__ __forceinline__ void fox_unit(int b, int hh, int qb, const bf16_t* Q, const bf16_t* __restrict__ K, const bf16_t* __restrict__ V, bf16_t* O, ...
;     ...
;         if (jp == NT / 2 - 1) { unsigned a = 0;
; #pragma unroll
;             for (int w = 0; w < 8; ++w) a |= flags[w];
;             excess = __builtin_amdgcn_readfirstlane(a) != 0u; }
;         const bool last = (jp == (excess ? 0 : jp_last0));
;         if (!last) { FOX_DMA(2 * jp - 1, (2 * jp - 1) & 3); FOX_DMA(2 * jp - 2, (2 * jp - 2) & 3); }
; #pragma unroll
;     ...
;         if (64 * jt <= qw0 + 31 && (excess || jp >= jp_lastw)) {
;             const LAS3 unsigned char* kp = kp0 + slot * SLOTB; const LAS3 unsigned char* fp = fp0 + slot * 1024;
;             asm volatile("" : "+v"(cinit));
;             f32x16 p0 = __builtin_amdgcn_mfma_f32_32x32x16_bf16(*(const LAS3 bf16x8*)(fp), qones, cinit, 0, 0, 0);
;             f32x16 p1 = __builtin_amdgcn_mfma_f32_32x32x16_bf16(*(const LAS3 bf16x8*)(fp + 512), qones, cinit, 0, 0, 0);
; #pragma unroll
;             for (int d0 = 0; d0 < 4; ++d0) {
;                 const bf16x8 k0 = *(const LAS3 bf16x8*)(kp + d0 * 2048), k1 = *(const LAS3 bf16x8*)(kp + d0 * 2048 + 512);
;                 p0 = __builtin_amdgcn_mfma_f32_32x32x16_bf16(k0, qr[d0], p0, 0, 0, 0);
;                 p1 = __builtin_amdgcn_mfma_f32_32x32x16_bf16(k1, qr[d0], p1, 0, 0, 0);
;             }
;             if (64 * jt + 63 > qw0) { const int kb_ = 64 * jt + 4 * hi - (qw0 + r32);
; __global__ void __launch_bounds__(NWAVES * 64, 2) fwd_megakernel(Args args) {
;     ...
;             if (tid == 0) qw[0] = atomicAdd(CTL, 1u);
.LBB0_422:
	s_add_i32 s3, s88, s3
	s_or_b64 s[12:13], s[10:11], s[84:85]
	s_and_b64 s[12:13], s[12:13], exec
	s_cselect_b32 s7, 0, s75
	s_cmp_lg_u32 s3, s7
	s_cselect_b64 s[86:87], -1, 0
	s_cbranch_scc1 .Lqpf_notlast
	s_mov_b64 s[98:99], exec
	v_readlane_b32 s100, v249, 10
	v_readlane_b32 s101, v249, 11
	s_nop 0
	s_and_b64 exec, s[98:99], s[100:101]
	s_cbranch_execz .Lqpf_skip1
	v_readlane_b32 s100, v249, 43
	v_readlane_b32 s101, v249, 44
	v_mov_b32_e32 v187, 1
	s_nop 3
	global_atomic_add v187, v3, v187, s[100:101] sc0
.Lqpf_skip1:
	s_mov_b64 exec, s[98:99]
.Lqpf_notlast:
.LBB0_427:
	s_cmp_ge_i32 s3, s74
	s_cselect_b64 s[12:13], -1, 0
	s_or_b64 s[94:95], s[84:85], s[12:13]
	s_add_i32 s12, s96, s71
	s_add_i32 s7, s12, 0x1fc0
	s_cmp_le_u32 s7, s33
	s_cselect_b64 s[14:15], -1, 0
	s_and_b64 s[14:15], s[14:15], s[94:95]
	s_andn2_b64 vcc, exec, s[14:15]
	s_cbranch_vccnz .LBB0_431
	s_add_i32 s7, s6, -1
	s_and_b32 s7, s7, 3
	v_lshl_add_u32 v2, s7, 10, v166
	ds_read_b128 v[188:191], v2
	ds_read_b128 v[192:195], v2 offset:512
	s_lshl_b32 s7, s7, 13
	v_add_u32_e32 v2, s7, v137
	ds_read_b128 v[196:199], v2
	ds_read_b128 v[200:203], v2 offset:512
	ds_read_b128 v[204:207], v2 offset:2048
	ds_read_b128 v[208:211], v2 offset:2560
	ds_read_b128 v[212:215], v2 offset:4096
	ds_read_b128 v[216:219], v2 offset:4608
	ds_read_b128 v[220:223], v2 offset:6144
	ds_read_b128 v[224:227], v2 offset:6656
	s_addk_i32 s12, 0x1fff
	s_cmp_le_u32 s12, s70
	v_add_u32_e32 v186, s7, v165
	s_waitcnt lgkmcnt(9)
	v_mfma_f32_32x32x16_bf16 v[82:97], v[188:191], v[114:117], v[50:65]
	s_waitcnt lgkmcnt(8)
	v_mfma_f32_32x32x16_bf16 v[98:113], v[192:195], v[114:117], v[50:65]
	s_waitcnt lgkmcnt(7)
	v_mfma_f32_32x32x16_bf16 v[82:97], v[196:199], v[118:121], v[82:97]
	s_waitcnt lgkmcnt(6)
	v_mfma_f32_32x32x16_bf16 v[98:113], v[200:203], v[118:121], v[98:113]
	s_waitcnt lgkmcnt(5)
	v_mfma_f32_32x32x16_bf16 v[82:97], v[204:207], v[122:125], v[82:97]
	s_waitcnt lgkmcnt(4)
	v_mfma_f32_32x32x16_bf16 v[98:113], v[208:211], v[122:125], v[98:113]
	s_waitcnt lgkmcnt(3)
	v_mfma_f32_32x32x16_bf16 v[82:97], v[212:215], v[126:129], v[82:97]
	s_waitcnt lgkmcnt(2)
	v_mfma_f32_32x32x16_bf16 v[98:113], v[216:219], v[126:129], v[98:113]
	s_waitcnt lgkmcnt(1)
	v_mfma_f32_32x32x16_bf16 v[82:97], v[220:223], v[130:133], v[82:97]
	s_waitcnt lgkmcnt(0)
	v_mfma_f32_32x32x16_bf16 v[98:113], v[224:227], v[130:133], v[98:113]
	ds_read_b64_tr_b16 v[188:189], v186 offset:32768
	ds_read_b64_tr_b16 v[190:191], v186 offset:33280
	ds_read_b64_tr_b16 v[192:193], v186 offset:36864
	ds_read_b64_tr_b16 v[194:195], v186 offset:37376
	ds_read_b64_tr_b16 v[196:197], v186 offset:33792
	ds_read_b64_tr_b16 v[198:199], v186 offset:34304
	ds_read_b64_tr_b16 v[200:201], v186 offset:37888
	ds_read_b64_tr_b16 v[202:203], v186 offset:38400
	ds_read_b64_tr_b16 v[204:205], v186 offset:34816
	ds_read_b64_tr_b16 v[206:207], v186 offset:35328
	ds_read_b64_tr_b16 v[208:209], v186 offset:38912
	ds_read_b64_tr_b16 v[210:211], v186 offset:39424
	ds_read_b64_tr_b16 v[212:213], v186 offset:35840
	ds_read_b64_tr_b16 v[214:215], v186 offset:36352
	ds_read_b64_tr_b16 v[216:217], v186 offset:39936
	ds_read_b64_tr_b16 v[218:219], v186 offset:40448
	s_cbranch_scc1 .LBB0_430
; __device__ __forceinline__ void fox_unit(int b, int hh, int qb, const bf16_t* Q, const bf16_t* __restrict__ K, const bf16_t* __restrict__ V, bf16_t* O, ...
;     ...
;             if (64 * jt + 63 > qw0) { const int kb_ = 64 * jt + 4 * hi - (qw0 + r32);
; #pragma unroll
;                 for (int r = 0; r < 16; ++r) { const int cr = (r & 3) + 8 * (r >> 2); if (kb_ + cr > 0) p0[r] = -INFINITY; if (kb_ + cr + 32 > 0) p1[r] = -INFINITY; } }
	v_add_u32_e32 v2, s71, v155
	v_add_u32_e32 v2, 0xc0, v2
	s_movk_i32 s40, 0xffe6
	s_movk_i32 s68, 0xffe5
	s_movk_i32 s38, 0xffe7
	v_cmp_lt_i32_e64 s[66:67], s40, v2
	v_cmp_lt_i32_e64 s[68:69], s68, v2
	s_movk_i32 s36, 0xffe8
	v_cmp_lt_i32_e64 s[64:65], s38, v2
	s_and_b64 s[66:67], s[68:69], s[66:67]
	s_movk_i32 s34, 0xffed
	v_cmp_lt_i32_e64 s[62:63], s36, v2
	s_and_b64 s[64:65], s[66:67], s[64:65]
	s_movk_i32 s30, 0xffee
	v_cmp_lt_i32_e64 s[60:61], s34, v2
	s_and_b64 s[62:63], s[64:65], s[62:63]
	s_movk_i32 s28, 0xffef
	v_cmp_lt_i32_e64 s[58:59], s30, v2
	s_and_b64 s[60:61], s[62:63], s[60:61]
	v_cmp_lt_i32_e64 s[56:57], s28, v2
	s_and_b64 s[58:59], s[60:61], s[58:59]
	v_cmp_lt_i32_e64 s[54:55], -16, v2
	s_and_b64 s[56:57], s[58:59], s[56:57]
	v_cmp_lt_i32_e64 s[52:53], -11, v2
	s_and_b64 s[54:55], s[56:57], s[54:55]
	v_cmp_lt_i32_e64 s[50:51], -10, v2
	s_and_b64 s[52:53], s[54:55], s[52:53]
	v_cmp_lt_i32_e64 s[48:49], -9, v2
	s_and_b64 s[50:51], s[52:53], s[50:51]
	s_movk_i32 s14, 0xffe0
	v_cmp_lt_i32_e64 s[46:47], -8, v2
	s_and_b64 s[48:49], s[50:51], s[48:49]
	v_cmp_gt_i32_e64 s[12:13], 1, v2
	v_cmp_lt_i32_e32 vcc, s14, v2
	v_cmp_gt_i32_e64 s[14:15], 0, v2
	v_cmp_lt_i32_e64 s[44:45], -3, v2
	s_and_b64 s[46:47], s[48:49], s[46:47]
	s_or_b64 s[12:13], s[14:15], s[12:13]
	v_cmp_lt_i32_e64 s[42:43], -2, v2
	s_and_b64 s[44:45], s[46:47], s[44:45]
	v_cndmask_b32_e64 v4, v174, v83, s[14:15]
	v_cndmask_b32_e64 v5, v174, v82, s[12:13]
	s_and_b64 s[42:43], s[44:45], s[42:43]
	s_movk_i32 s40, 0xffc6
	v_cndmask_b32_e64 v82, v82, v5, s[42:43]
	v_cndmask_b32_e64 v84, v84, v174, s[42:43]
	v_cndmask_b32_e64 v83, v83, v4, s[42:43]
	s_movk_i32 s42, 0xffc5
	s_movk_i32 s38, 0xffc7
	v_cmp_lt_i32_e64 s[40:41], s40, v2
	v_cmp_lt_i32_e64 s[42:43], s42, v2
	s_movk_i32 s36, 0xffc8
	v_cmp_lt_i32_e64 s[38:39], s38, v2
	s_and_b64 s[40:41], s[42:43], s[40:41]
	s_movk_i32 s34, 0xffcd
	v_cmp_lt_i32_e64 s[36:37], s36, v2
	s_and_b64 s[38:39], s[40:41], s[38:39]
	s_movk_i32 s30, 0xffce
	v_cmp_lt_i32_e64 s[34:35], s34, v2
	s_and_b64 s[36:37], s[38:39], s[36:37]
	s_movk_i32 s28, 0xffcf
	v_cmp_lt_i32_e64 s[30:31], s30, v2
	s_and_b64 s[34:35], s[36:37], s[34:35]
	s_movk_i32 s26, 0xffd0
	v_cmp_lt_i32_e64 s[28:29], s28, v2
	s_and_b64 s[30:31], s[34:35], s[30:31]
	s_movk_i32 s24, 0xffd5
	v_cmp_lt_i32_e64 s[26:27], s26, v2
	s_and_b64 s[28:29], s[30:31], s[28:29]
	s_movk_i32 s22, 0xffd6
	v_cmp_lt_i32_e64 s[24:25], s24, v2
	s_and_b64 s[26:27], s[28:29], s[26:27]
	s_movk_i32 s20, 0xffd7
	v_cmp_lt_i32_e64 s[22:23], s22, v2
	s_and_b64 s[24:25], s[26:27], s[24:25]
	s_movk_i32 s18, 0xffd8
	v_cmp_lt_i32_e64 s[20:21], s20, v2
	s_and_b64 s[22:23], s[24:25], s[22:23]
	s_movk_i32 s16, 0xffdd
	v_cmp_lt_i32_e64 s[18:19], s18, v2
	s_and_b64 s[20:21], s[22:23], s[20:21]
	s_movk_i32 s14, 0xffde
	v_cmp_lt_i32_e64 s[16:17], s16, v2
	s_and_b64 s[18:19], s[20:21], s[18:19]
	s_movk_i32 s12, 0xffdf
	v_cmp_lt_i32_e64 s[14:15], s14, v2
	s_and_b64 s[16:17], s[18:19], s[16:17]
	v_cmp_lt_i32_e64 s[12:13], s12, v2
	s_and_b64 s[14:15], s[16:17], s[14:15]
	s_and_b64 s[12:13], s[14:15], s[12:13]
	s_and_b64 vcc, s[12:13], vcc
	v_cndmask_b32_e64 v97, v97, v174, s[68:69]
	v_cndmask_b32_e64 v96, v96, v174, s[66:67]
	v_cndmask_b32_e64 v95, v95, v174, s[64:65]
	v_cndmask_b32_e64 v94, v94, v174, s[62:63]
	v_cndmask_b32_e64 v93, v93, v174, s[60:61]
	v_cndmask_b32_e64 v92, v92, v174, s[58:59]
	v_cndmask_b32_e64 v91, v91, v174, s[56:57]
	v_cndmask_b32_e64 v90, v90, v174, s[54:55]
	v_cndmask_b32_e64 v89, v89, v174, s[52:53]
	v_cndmask_b32_e64 v88, v88, v174, s[50:51]
	v_cndmask_b32_e64 v87, v87, v174, s[48:49]
	v_cndmask_b32_e64 v86, v86, v174, s[46:47]
	v_cndmask_b32_e64 v85, v85, v174, s[44:45]
	v_cndmask_b32_e64 v113, v113, v174, s[42:43]
	v_cndmask_b32_e64 v112, v112, v174, s[40:41]
	v_cndmask_b32_e64 v111, v111, v174, s[38:39]
	v_cndmask_b32_e64 v110, v110, v174, s[36:37]
	v_cndmask_b32_e64 v109, v109, v174, s[34:35]
	v_cndmask_b32_e64 v108, v108, v174, s[30:31]
	v_cndmask_b32_e64 v107, v107, v174, s[28:29]
	v_cndmask_b32_e64 v106, v106, v174, s[26:27]
	v_cndmask_b32_e64 v105, v105, v174, s[24:25]
	v_cndmask_b32_e64 v104, v104, v174, s[22:23]
	v_cndmask_b32_e64 v103, v103, v174, s[20:21]
	v_cndmask_b32_e64 v102, v102, v174, s[18:19]
	v_cndmask_b32_e64 v101, v101, v174, s[16:17]
	v_cndmask_b32_e64 v100, v100, v174, s[14:15]
	v_cndmask_b32_e64 v99, v99, v174, s[12:13]
	v_cndmask_b32_e32 v98, v98, v174, vcc
